# attention tile loop: next tile's four Q fragment reads issued inside the last PV MFMA block before the tile barrier (halves the post-barrier LDS read burst)
# speedup vs baseline: 1.0057x; 1.0007x over previous
; #define LAS __attribute__((address_space(3)))
; template <bool SHIFT> DI void phase_attn2(const Params& p, const Grp& G, int layer, LAS unsigned char* lds, int tid, int wave, int lane, int vcu, bool dry) {
;     ...
;         const int qb = u % NQB, bh = u / NQB, h = bh & 3, b = bh >> 2; const size_t seq0 = (size_t)b * G.S; const size_t qrow0 = seq0 + (size_t)qb * 256;
;         bf16x8 qf[2][4];
;         int lq = (int)__builtin_amdgcn_mbcnt_hi(~0u, __builtin_amdgcn_mbcnt_lo(~0u, 0u)); asm volatile("" : "+v"(lq));
; #pragma unroll
;         for (int rbq = 0; rbq < 2; ++rbq) { const bf16_t* qp = mix + (qrow0 + 64 * qg + 32 * rbq + (lq & 31)) * MIXW + h * 128 + c * 64 + 8 * (lq >> 5);
; #pragma unroll
;           for (int d0 = 0; d0 < 4; ++d0) qf[rbq][d0] = *(const bf16x8*)(qp + 16 * d0); }
;         LAS unsigned char* Qs = lds + AT2_QS + wave * 8192 + lane * 16;
;         const bf16_t* kg = rest + seq0 * RESTW + R_DK + h * 128; const bf16_t* vg = rest + seq0 * RESTW + R_DV + h * 128;
;         __syncthreads();
;     ...
;         { unsigned dfl = doff0; asm volatile("" : "+v"(dfl)); AT2_DMA(0, 0); }
; #pragma unroll
;         for (int rbq = 0; rbq < 2; ++rbq)
; #pragma unroll
;             for (int d0 = 0; d0 < 4; ++d0) *(LAS bf16x8*)(Qs + (rbq * 4 + d0) * 1024) = qf[rbq][d0];
;         asm volatile("s_waitcnt vmcnt(0)" ::: "memory");
;         __syncthreads();
.LBB0_377:
	s_abs_i32 s1, s58
	s_mul_hi_u32 s8, s1, s55
	s_mul_i32 s9, s8, s53
	s_ashr_i32 s0, s58, 31
	s_sub_i32 s1, s1, s9
	s_xor_b32 s0, s0, s54
	s_add_i32 s9, s8, 1
	s_sub_i32 s10, s1, s53
	s_cmp_ge_u32 s1, s53
	s_cselect_b32 s8, s9, s8
	s_cselect_b32 s1, s10, s1
	s_add_i32 s9, s8, 1
	s_cmp_ge_u32 s1, s53
	s_cselect_b32 s1, s9, s8
	s_xor_b32 s1, s1, s0
	s_sub_i32 s10, s1, s0
	s_mul_i32 s0, s10, s14
	s_sub_i32 s8, s58, s0
	s_ashr_i32 s0, s10, 2
	s_ashr_i32 s1, s0, 31
	v_readlane_b32 s9, v255, 40
	s_lshl_b64 s[0:1], s[0:1], s9
	s_ashr_i32 s9, s8, 31
	s_lshl_b64 s[8:9], s[8:9], 8
	s_add_u32 s40, s0, s8
	s_addc_u32 s41, s1, s9
	v_mov_b32_e32 v2, v245
	s_lshl_b32 s8, s10, 7
	s_and_b32 s59, s8, 0x180
	v_and_or_b32 v0, v2, 31, s13
	s_lshl_b32 s11, s59, 1
	v_ashrrev_i32_e32 v2, 2, v2
	s_add_u32 s8, s16, s11
	v_and_b32_e32 v2, -8, v2
	s_addc_u32 s9, s17, 0
	v_ashrrev_i32_e32 v3, 31, v2
	v_lshl_add_u64 v[2:3], v[2:3], 1, s[8:9]
	s_mulk_i32 s1, 0x1400
	s_mul_hi_u32 s9, s0, 0x1400
	v_or_b32_e32 v0, s40, v0
	v_mov_b32_e32 v1, s41
	s_mul_i32 s30, s0, 0x1400
	s_add_i32 s9, s9, s1
	v_lshlrev_b64 v[0:1], 11, v[0:1]
	s_add_u32 s0, s48, s30
	v_lshl_add_u64 v[16:17], v[2:3], 0, v[0:1]
	s_mov_b32 s8, 0x10000
	s_addc_u32 s1, s49, s9
	v_add_co_u32_e32 v28, vcc, s8, v16
	s_add_u32 s0, s0, s11
	s_nop 0
	v_addc_co_u32_e32 v29, vcc, 0, v17, vcc
	v_mov_b32_e32 v192, v219
	s_addc_u32 s1, s1, 0
	s_mov_b32 m0, s33
	global_load_dwordx4 v[0:3], v[16:17], off
	global_load_dwordx4 v[4:7], v[16:17], off offset:32
	global_load_dwordx4 v[8:11], v[16:17], off offset:64
	global_load_dwordx4 v[12:15], v[16:17], off offset:96
	s_nop 0
	global_load_dwordx4 v[16:19], v[28:29], off
	global_load_dwordx4 v[20:23], v[28:29], off offset:32
	global_load_dwordx4 v[24:27], v[28:29], off offset:64
	s_nop 0
	global_load_dwordx4 v[28:31], v[28:29], off offset:96
	s_barrier
	s_mov_b64 s[84:85], 0x400
	v_lshl_add_u64 v[34:35], s[0:1], 0, v[192:193]
	global_load_lds_dwordx4 v192, s[0:1]
	s_add_i32 m0, s33, 0x4000
	v_lshl_add_u64 v[34:35], v[34:35], 0, s[84:85]
	v_mov_b32_e32 v33, v193
	v_xad_u32 v32, v192, 16, v244
	global_load_lds_dwordx4 v[34:35], off
	s_add_i32 m0, s33, 0x400
	v_lshl_add_u64 v[36:37], s[0:1], 0, v[32:33]
	global_load_lds_dwordx4 v32, s[0:1]
	v_readlane_b32 s0, v254, 37
	v_lshl_add_u64 v[34:35], v[36:37], 0, s[84:85]
	s_mov_b32 m0, s0
	s_and_b32 s10, s10, 3
	global_load_lds_dwordx4 v[34:35], off
	s_lshl_b32 s10, s10, 8
	s_or_b32 s10, s30, s10
	v_mov_b32_e32 v64, 0
	s_add_u32 s30, s56, s10
	s_mov_b32 s8, 0
	v_mov_b32_e32 v222, v221
	s_mov_b32 s38, 0
	v_mov_b32_e32 v65, v64
	v_mov_b32_e32 v66, v64
	s_addc_u32 s31, s57, s9
	v_mov_b32_e32 v67, v64
	v_mov_b32_e32 v68, v64
	v_mov_b32_e32 v69, v64
	v_mov_b32_e32 v70, v64
	v_mov_b32_e32 v71, v64
	v_mov_b32_e32 v72, v64
	v_mov_b32_e32 v73, v64
	v_mov_b32_e32 v74, v64
	v_mov_b32_e32 v75, v64
	v_mov_b32_e32 v76, v64
	v_mov_b32_e32 v77, v64
	v_mov_b32_e32 v78, v64
	v_mov_b32_e32 v79, v64
	v_mov_b32_e32 v80, v64
	s_waitcnt vmcnt(0)
	ds_write_b128 v221, v[0:3]
	ds_write_b128 v221, v[4:7] offset:1024
	ds_write_b128 v221, v[8:11] offset:2048
	ds_write_b128 v221, v[12:15] offset:3072
	ds_write_b128 v221, v[16:19] offset:4096
	ds_write_b128 v221, v[20:23] offset:5120
	ds_write_b128 v221, v[24:27] offset:6144
	ds_write_b128 v221, v[28:31] offset:7168
	s_waitcnt vmcnt(0)
	v_mov_b32_e32 v81, v64
	v_mov_b32_e32 v82, v64
	v_mov_b32_e32 v83, v64
	v_mov_b32_e32 v84, v64
	v_mov_b32_e32 v85, v64
	v_mov_b32_e32 v86, v64
	v_mov_b32_e32 v87, v64
	v_mov_b32_e32 v88, v64
	v_mov_b32_e32 v89, v64
	v_mov_b32_e32 v90, v64
	v_mov_b32_e32 v91, v64
	v_mov_b32_e32 v92, v64
	v_mov_b32_e32 v93, v64
	v_mov_b32_e32 v94, v64
	v_mov_b32_e32 v95, v64
	v_mov_b32_e32 v96, v64
	v_mov_b32_e32 v97, v64
	v_mov_b32_e32 v98, v64
	v_mov_b32_e32 v99, v64
	v_mov_b32_e32 v100, v64
	v_mov_b32_e32 v101, v64
	v_mov_b32_e32 v102, v64
	v_mov_b32_e32 v103, v64
	v_mov_b32_e32 v104, v64
	v_mov_b32_e32 v105, v64
	v_mov_b32_e32 v106, v64
	v_mov_b32_e32 v107, v64
	v_mov_b32_e32 v108, v64
	v_mov_b32_e32 v109, v64
	v_mov_b32_e32 v110, v64
	v_mov_b32_e32 v111, v64
	v_mov_b32_e32 v112, v64
	v_mov_b32_e32 v113, v64
	v_mov_b32_e32 v114, v64
	v_mov_b32_e32 v115, v64
	v_mov_b32_e32 v116, v64
	v_mov_b32_e32 v117, v64
	v_mov_b32_e32 v118, v64
	v_mov_b32_e32 v119, v64
	v_mov_b32_e32 v120, v64
	v_mov_b32_e32 v121, v64
	v_mov_b32_e32 v122, v64
	v_mov_b32_e32 v123, v64
	v_mov_b32_e32 v124, v64
	v_mov_b32_e32 v125, v64
	v_mov_b32_e32 v126, v64
	v_mov_b32_e32 v127, v64
	v_mov_b32_e32 v0, v64
	v_mov_b32_e32 v1, v64
	v_mov_b32_e32 v2, v64
	v_mov_b32_e32 v3, v64
	v_mov_b32_e32 v4, v64
	v_mov_b32_e32 v5, v64
	v_mov_b32_e32 v6, v64
	v_mov_b32_e32 v7, v64
	v_mov_b32_e32 v8, v64
	v_mov_b32_e32 v9, v64
	v_mov_b32_e32 v10, v64
	v_mov_b32_e32 v11, v64
	v_mov_b32_e32 v12, v64
	v_mov_b32_e32 v13, v64
	v_mov_b32_e32 v14, v64
	v_mov_b32_e32 v15, v64
	v_mov_b32_e32 v16, v64
	v_mov_b32_e32 v17, v64
	v_mov_b32_e32 v18, v64
	v_mov_b32_e32 v19, v64
	v_mov_b32_e32 v20, v64
	v_mov_b32_e32 v21, v64
	v_mov_b32_e32 v22, v64
	v_mov_b32_e32 v23, v64
	v_mov_b32_e32 v24, v64
	v_mov_b32_e32 v25, v64
	v_mov_b32_e32 v26, v64
	v_mov_b32_e32 v27, v64
	v_mov_b32_e32 v28, v64
	v_mov_b32_e32 v29, v64
	v_mov_b32_e32 v30, v64
	v_mov_b32_e32 v31, v64
	v_mov_b32_e32 v32, v64
	v_mov_b32_e32 v33, v64
	v_mov_b32_e32 v34, v64
	v_mov_b32_e32 v35, v64
	v_mov_b32_e32 v36, v64
	v_mov_b32_e32 v37, v64
	v_mov_b32_e32 v38, v64
	v_mov_b32_e32 v39, v64
	v_mov_b32_e32 v40, v64
	v_mov_b32_e32 v41, v64
	v_mov_b32_e32 v42, v64
	v_mov_b32_e32 v43, v64
	v_mov_b32_e32 v44, v64
	v_mov_b32_e32 v45, v64
	v_mov_b32_e32 v46, v64
	v_mov_b32_e32 v47, v64
	v_mov_b32_e32 v48, v64
	v_mov_b32_e32 v49, v64
	v_mov_b32_e32 v50, v64
	v_mov_b32_e32 v51, v64
	v_mov_b32_e32 v52, v64
	v_mov_b32_e32 v53, v64
	v_mov_b32_e32 v54, v64
	v_mov_b32_e32 v55, v64
	v_mov_b32_e32 v56, v64
	v_mov_b32_e32 v57, v64
	v_mov_b32_e32 v58, v64
	v_mov_b32_e32 v59, v64
	v_mov_b32_e32 v60, v64
	v_mov_b32_e32 v61, v64
	v_mov_b32_e32 v62, v64
	v_mov_b32_e32 v63, v64
	v_mov_b32_e32 v164, v64
	v_mov_b32_e32 v165, v64
	v_xor_b32_e32 v236, 32, v217
	v_xor_b32_e32 v237, 64, v217
	v_xor_b32_e32 v238, 0x60, v217
	v_xor_b32_e32 v239, 32, v218
	v_xor_b32_e32 v240, 64, v218
	v_xor_b32_e32 v241, 0x60, v218
	v_xor_b32_e32 v248, 0x80, v218
	v_xor_b32_e32 v249, 0xa0, v218
	v_xor_b32_e32 v250, 0xc0, v218
	v_xor_b32_e32 v251, 0xe0, v218
	v_xad_u32 v252, v219, 16, v244
	s_waitcnt lgkmcnt(0)
	s_barrier
	ds_read_b128 v[132:135], v222
	ds_read_b128 v[136:139], v222 offset:1024
	ds_read_b128 v[140:143], v222 offset:2048
	ds_read_b128 v[174:177], v222 offset:3072
	s_branch .LBB0_379
; #define SB() __builtin_amdgcn_sched_barrier(0)
; #define EXPACK(sc_, rbq_, p0_, p1_) do { float ps_ = 0.f; \
;                 _Pragma("unroll") for (int r = 0; r < 16; ++r) { sc_[r] = __builtin_amdgcn_exp2f(SHIFT ? sc_[r] - bound2 : sc_[r]); ps_ += sc_[r]; } \
;                 lsum[rbq_] += ps_; p0_ = pack8(sc_, 0); p1_ = pack8(sc_, 1); } while (0)
; #define BLOAD(B_, ks_) do { asm volatile("" : "+v"(v0l)); _Pragma("unroll") for (int cb = 0; cb < 4; ++cb) B_[cb] = BFRAG(ks_, cb); SB(); } while (0)
; #define PVMMA(B_, pA_, pB_) do { _Pragma("unroll") for (int cb = 0; cb < 4; ++cb) { o[0][cb] = MFMA32(pA_, B_[cb], o[0][cb]); o[1][cb] = MFMA32(pB_, B_[cb], o[1][cb]); } } while (0)
; template <bool SHIFT> DI void phase_attn2(const Params& p, const Grp& G, int layer, LAS unsigned char* lds, int tid, int wave, int lane, int vcu, bool dry) {
;     ...
;             {
;                 f32x16 s0, s1; bf16x8 pa00, pa01, pa10, pa11; bf16x8 kfs[4], qfs[4];
;                 CHAIN(s0, 0, 0, true, true); CHAIN(s1, 0, 1, false, true);
;                 EXPACK(s0, 0, pa00, pa01); EXPACK(s1, 1, pa10, pa11);
;                 SB();
;                 CHAIN(s1, 1, 1, true, false); CHAIN(s0, 1, 0, false, true);
;                 bf16x8 pb00, pb01, pb10, pb11; bf16x8 B[4];
;                 BLOAD(B, 0);
;                 PVMMA(B, pa00, pa10); EXPACK(s0, 0, pb00, pb01);
.LBB0_378:
	s_waitcnt lgkmcnt(0)
	v_mfma_f32_32x32x16_bf16 v[144:159], v[128:131], v[132:135], 0
	v_mfma_f32_32x32x16_bf16 v[144:159], v[160:163], v[136:139], v[144:159]
	v_mfma_f32_32x32x16_bf16 v[144:159], v[166:169], v[140:143], v[144:159]
	v_mfma_f32_32x32x16_bf16 v[144:159], v[170:173], v[174:177], v[144:159]
	ds_read_b128 v[174:177], v222 offset:4096
	ds_read_b128 v[178:181], v222 offset:5120
	ds_read_b128 v[182:185], v222 offset:6144
	ds_read_b128 v[224:227], v222 offset:7168
	s_waitcnt lgkmcnt(0)
	v_mfma_f32_32x32x16_bf16 v[128:143], v[128:131], v[174:177], 0
	v_mfma_f32_32x32x16_bf16 v[128:143], v[160:163], v[178:181], v[128:143]
	v_mfma_f32_32x32x16_bf16 v[128:143], v[166:169], v[182:185], v[128:143]
	v_mfma_f32_32x32x16_bf16 v[128:143], v[170:173], v[224:227], v[128:143]
	ds_read_b128 v[170:173], v236 offset:8192
	ds_read_b128 v[228:231], v237 offset:8192
	ds_read_b128 v[232:235], v238 offset:8192
	v_exp_f32_e32 v144, v144
	v_exp_f32_e32 v145, v145
	v_exp_f32_e32 v146, v146
	v_exp_f32_e32 v147, v147
	v_exp_f32_e32 v148, v148
	v_exp_f32_e32 v149, v149
	v_exp_f32_e32 v150, v150
	v_exp_f32_e32 v188, v151
	v_exp_f32_e32 v208, v152
	v_exp_f32_e32 v206, v153
	v_exp_f32_e32 v204, v154
	v_exp_f32_e32 v202, v155
	v_exp_f32_e32 v200, v156
	v_exp_f32_e32 v198, v157
	v_exp_f32_e32 v196, v158
	v_exp_f32_e32 v190, v159
	v_exp_f32_e32 v189, v135
	v_add_f32_e32 v135, v145, v144
	v_exp_f32_e32 v128, v128
	v_exp_f32_e32 v129, v129
	v_exp_f32_e32 v130, v130
	v_exp_f32_e32 v131, v131
	v_exp_f32_e32 v132, v132
	v_exp_f32_e32 v133, v133
	v_exp_f32_e32 v134, v134
	v_add_f32_e32 v135, v146, v135
	v_add_f32_e32 v135, v147, v135
	v_add_f32_e32 v135, v148, v135
	v_add_f32_e32 v135, v149, v135
	v_cvt_pk_bf16_f32 v160, v144, v145
	v_cvt_pk_bf16_f32 v161, v146, v147
	v_cvt_pk_bf16_f32 v162, v148, v149
	v_cvt_pk_bf16_f32 v163, v150, v188
	v_exp_f32_e32 v209, v136
	v_exp_f32_e32 v207, v137
	v_exp_f32_e32 v205, v138
	v_exp_f32_e32 v203, v139
	v_exp_f32_e32 v201, v140
	v_exp_f32_e32 v199, v141
	v_exp_f32_e32 v197, v142
	v_exp_f32_e32 v191, v143
	v_add_f32_e32 v210, v150, v135
	v_cvt_pk_bf16_f32 v166, v128, v129
	v_cvt_pk_bf16_f32 v167, v130, v131
	v_cvt_pk_bf16_f32 v168, v132, v133
	v_cvt_pk_bf16_f32 v169, v134, v189
	ds_read_b128 v[144:147], v217 offset:8192
	v_add_f32_e32 v128, v129, v128
	v_add_f32_e32 v128, v130, v128
	v_add_f32_e32 v128, v131, v128
	v_add_f32_e32 v128, v132, v128
	v_add_f32_e32 v128, v133, v128
	v_add_f32_e32 v211, v134, v128
	s_waitcnt lgkmcnt(0)
	v_mfma_f32_32x32x16_bf16 v[128:143], v[144:147], v[174:177], 0
	v_mfma_f32_32x32x16_bf16 v[128:143], v[170:173], v[178:181], v[128:143]
	v_mfma_f32_32x32x16_bf16 v[128:143], v[228:231], v[182:185], v[128:143]
	v_mfma_f32_32x32x16_bf16 v[128:143], v[232:235], v[224:227], v[128:143]
	ds_read_b128 v[148:151], v222
	ds_read_b128 v[174:177], v222 offset:1024
	ds_read_b128 v[178:181], v222 offset:2048
	ds_read_b128 v[182:185], v222 offset:3072
	s_waitcnt lgkmcnt(0)
	v_mfma_f32_32x32x16_bf16 v[144:159], v[144:147], v[148:151], 0
	v_mfma_f32_32x32x16_bf16 v[144:159], v[170:173], v[174:177], v[144:159]
	v_mfma_f32_32x32x16_bf16 v[144:159], v[228:231], v[178:181], v[144:159]
	v_mfma_f32_32x32x16_bf16 v[144:159], v[232:235], v[182:185], v[144:159]
	s_nop 4
	ds_read_b64_tr_b16 v[170:171], v218 offset:16384
	ds_read_b64_tr_b16 v[172:173], v239 offset:18432
	ds_read_b64_tr_b16 v[174:175], v240 offset:16384
	ds_read_b64_tr_b16 v[176:177], v241 offset:18432
	ds_read_b64_tr_b16 v[178:179], v248 offset:16384
	ds_read_b64_tr_b16 v[180:181], v249 offset:18432
	ds_read_b64_tr_b16 v[182:183], v250 offset:16384
	ds_read_b64_tr_b16 v[184:185], v251 offset:18432
	v_exp_f32_e32 v144, v144
	s_waitcnt lgkmcnt(6)
	v_mfma_f32_32x32x16_bf16 v[112:127], v[160:163], v[170:173], v[112:127]
	v_exp_f32_e32 v145, v145
	v_exp_f32_e32 v146, v146
	v_exp_f32_e32 v147, v147
	v_exp_f32_e32 v148, v148
	v_exp_f32_e32 v149, v149
	v_mfma_f32_32x32x16_bf16 v[0:15], v[166:169], v[170:173], v[0:15]
	v_exp_f32_e32 v170, v151
	v_exp_f32_e32 v172, v154
	s_waitcnt lgkmcnt(4)
	v_mfma_f32_32x32x16_bf16 v[96:111], v[160:163], v[174:177], v[96:111]
	v_mfma_f32_32x32x16_bf16 v[16:31], v[166:169], v[174:177], v[16:31]
	v_exp_f32_e32 v174, v153
	v_exp_f32_e32 v176, v156
	s_waitcnt lgkmcnt(2)
	v_mfma_f32_32x32x16_bf16 v[80:95], v[160:163], v[178:181], v[80:95]
	v_mfma_f32_32x32x16_bf16 v[32:47], v[166:169], v[178:181], v[32:47]
	v_exp_f32_e32 v178, v155
	v_exp_f32_e32 v180, v158
	s_waitcnt lgkmcnt(0)
	v_mfma_f32_32x32x16_bf16 v[64:79], v[160:163], v[182:185], v[64:79]
	v_add_f32_e32 v160, v145, v144
	v_add_f32_e32 v160, v146, v160
	v_add_f32_e32 v160, v147, v160
	v_add_f32_e32 v160, v148, v160
	v_add_f32_e32 v186, v149, v160
	v_cvt_pk_bf16_f32 v144, v144, v145
	v_mfma_f32_32x32x16_bf16 v[48:63], v[166:169], v[182:185], v[48:63]
	v_exp_f32_e32 v166, v150
	v_exp_f32_e32 v168, v152
	v_exp_f32_e32 v182, v157
	v_exp_f32_e32 v184, v159
	v_cvt_pk_bf16_f32 v145, v146, v147
	v_cvt_pk_bf16_f32 v146, v148, v149
	s_nop 0
	ds_read_b64_tr_b16 v[160:161], v218 offset:20480
	ds_read_b64_tr_b16 v[162:163], v239 offset:22528
	ds_read_b64_tr_b16 v[156:157], v240 offset:20480
	ds_read_b64_tr_b16 v[158:159], v241 offset:22528
	ds_read_b64_tr_b16 v[152:153], v248 offset:20480
	ds_read_b64_tr_b16 v[154:155], v249 offset:22528
	ds_read_b64_tr_b16 v[148:149], v250 offset:20480
	ds_read_b64_tr_b16 v[150:151], v251 offset:22528
	v_exp_f32_e32 v223, v128
	v_exp_f32_e32 v224, v129
	v_exp_f32_e32 v225, v130
	v_exp_f32_e32 v226, v131
	v_exp_f32_e32 v227, v132
	v_add_f32_e32 v128, v224, v223
	v_exp_f32_e32 v228, v133
	v_exp_f32_e32 v167, v134
	v_exp_f32_e32 v171, v135
	v_cvt_pk_bf16_f32 v132, v208, v206
	v_cvt_pk_bf16_f32 v133, v204, v202
	v_cvt_pk_bf16_f32 v134, v200, v198
	v_cvt_pk_bf16_f32 v135, v196, v190
	v_add_f32_e32 v128, v225, v128
	v_exp_f32_e32 v169, v136
	v_exp_f32_e32 v175, v137
	v_exp_f32_e32 v173, v138
	v_exp_f32_e32 v179, v139
	v_cvt_pk_bf16_f32 v136, v209, v207
	v_cvt_pk_bf16_f32 v137, v205, v203
	v_cvt_pk_bf16_f32 v138, v201, v199
	v_cvt_pk_bf16_f32 v139, v197, v191
	v_add_f32_e32 v128, v226, v128
	v_add_f32_e32 v128, v227, v128
	v_add_f32_e32 v187, v228, v128
	v_pk_add_f32 v[128:129], v[188:189], v[210:211]
	s_waitcnt lgkmcnt(6)
; #define LAS __attribute__((address_space(3)))
; #define SB() __builtin_amdgcn_sched_barrier(0)
; #define BLOAD(B_, ks_) do { asm volatile("" : "+v"(v0l)); _Pragma("unroll") for (int cb = 0; cb < 4; ++cb) B_[cb] = BFRAG(ks_, cb); SB(); } while (0)
; #define PVMMA(B_, pA_, pB_) do { _Pragma("unroll") for (int cb = 0; cb < 4; ++cb) { o[0][cb] = MFMA32(pA_, B_[cb], o[0][cb]); o[1][cb] = MFMA32(pB_, B_[cb], o[1][cb]); } } while (0)
; template <bool SHIFT> DI void phase_attn2(const Params& p, const Grp& G, int layer, LAS unsigned char* lds, int tid, int wave, int lane, int vcu, bool dry) {
;     ...
;         for (int t = 0; t < NT; ++t) {
;             unsigned dfl = doff0; asm volatile("" : "+v"(dfl));
;             if (t + 1 < NT) AT2_DMA(t + 1, (t + 1) & 1);
;             const LAS unsigned char* Kt = lds + (t & 1) * AT2_BUF; const LAS unsigned char* Vt = Kt + AT2_TILE;
;             int k0l = k0, v0l = v0; asm volatile("" : "+v"(k0l), "+v"(v0l));
;     ...
;                 BLOAD(B, 3);
;                 PVMMA(B, pb01, pb11);
;                 SB();
;             }
;     ...
;             asm volatile("s_waitcnt vmcnt(0)" ::: "memory");
;             __syncthreads();
	v_mfma_f32_32x32x16_bf16 v[112:127], v[132:135], v[160:163], v[112:127]
	v_add_f32_e64 v128, v208, v128
	v_add_f32_e64 v129, v209, v129
	v_exp_f32_e32 v177, v140
	v_pk_add_f32 v[128:129], v[206:207], v[128:129]
	v_exp_f32_e32 v183, v141
	v_pk_add_f32 v[128:129], v[204:205], v[128:129]
	v_exp_f32_e32 v181, v142
	v_pk_add_f32 v[128:129], v[202:203], v[128:129]
	s_waitcnt lgkmcnt(4)
	v_mfma_f32_32x32x16_bf16 v[96:111], v[132:135], v[156:159], v[96:111]
	v_exp_f32_e32 v185, v143
	v_pk_add_f32 v[128:129], v[200:201], v[128:129]
	v_cvt_pk_bf16_f32 v147, v166, v170
	v_pk_add_f32 v[128:129], v[198:199], v[128:129]
	v_cvt_pk_bf16_f32 v130, v176, v182
	v_pk_add_f32 v[128:129], v[196:197], v[128:129]
	v_cvt_pk_bf16_f32 v131, v180, v184
	s_waitcnt lgkmcnt(2)
	v_mfma_f32_32x32x16_bf16 v[80:95], v[132:135], v[152:155], v[80:95]
	v_add_f32_e64 v128, v190, v128
	v_add_f32_e64 v129, v191, v129
	v_add_f32_e64 v140, v164, v128
	v_add_f32_e64 v141, v165, v129
	v_cvt_pk_bf16_f32 v128, v168, v174
	v_cvt_pk_bf16_f32 v129, v172, v178
	s_waitcnt lgkmcnt(0)
	v_mfma_f32_32x32x16_bf16 v[64:79], v[132:135], v[148:151], v[64:79]
	v_add_f32_e64 v132, v166, v186
	v_add_f32_e64 v133, v167, v187
	v_cvt_pk_bf16_f32 v134, v227, v228
	v_add_f32_e64 v132, v170, v132
	v_add_f32_e64 v133, v171, v133
	v_cvt_pk_bf16_f32 v135, v167, v171
	v_pk_add_f32 v[132:133], v[168:169], v[132:133]
	s_nop 0
	v_pk_add_f32 v[132:133], v[174:175], v[132:133]
	v_mfma_f32_32x32x16_bf16 v[0:15], v[136:139], v[160:163], v[0:15]
	v_add_f32_e64 v132, v172, v132
	v_add_f32_e64 v133, v173, v133
	v_add_f32_e64 v132, v178, v132
	v_add_f32_e64 v133, v179, v133
	v_add_f32_e64 v132, v176, v132
	v_add_f32_e64 v133, v177, v133
	v_pk_add_f32 v[132:133], v[182:183], v[132:133]
	v_mfma_f32_32x32x16_bf16 v[16:31], v[136:139], v[156:159], v[16:31]
	v_add_f32_e64 v132, v180, v132
	v_add_f32_e64 v133, v181, v133
	v_add_f32_e64 v142, v184, v132
	v_add_f32_e64 v143, v185, v133
	v_cvt_pk_bf16_f32 v132, v223, v224
	v_cvt_pk_bf16_f32 v133, v225, v226
	v_mfma_f32_32x32x16_bf16 v[32:47], v[136:139], v[152:155], v[32:47]
	v_mfma_f32_32x32x16_bf16 v[48:63], v[136:139], v[148:151], v[48:63]
	v_cvt_pk_bf16_f32 v136, v169, v175
	v_cvt_pk_bf16_f32 v137, v173, v179
	v_cvt_pk_bf16_f32 v138, v177, v183
	v_cvt_pk_bf16_f32 v139, v181, v185
	s_nop 0
	ds_read_b64_tr_b16 v[148:149], v218 offset:24576
	ds_read_b64_tr_b16 v[150:151], v239 offset:26624
	ds_read_b64_tr_b16 v[152:153], v240 offset:24576
	ds_read_b64_tr_b16 v[154:155], v241 offset:26624
	ds_read_b64_tr_b16 v[156:157], v248 offset:24576
	ds_read_b64_tr_b16 v[158:159], v249 offset:26624
	ds_read_b64_tr_b16 v[160:161], v250 offset:24576
	ds_read_b64_tr_b16 v[162:163], v251 offset:26624
	s_waitcnt lgkmcnt(6)
	v_mfma_f32_32x32x16_bf16 v[112:127], v[144:147], v[148:151], v[112:127]
	v_add_f32_e64 v164, v140, v142
	v_add_f32_e64 v165, v141, v143
	v_mfma_f32_32x32x16_bf16 v[0:15], v[132:135], v[148:151], v[0:15]
	s_waitcnt lgkmcnt(4)
	v_mfma_f32_32x32x16_bf16 v[96:111], v[144:147], v[152:155], v[96:111]
	v_mfma_f32_32x32x16_bf16 v[16:31], v[132:135], v[152:155], v[16:31]
	s_waitcnt lgkmcnt(2)
	v_mfma_f32_32x32x16_bf16 v[80:95], v[144:147], v[156:159], v[80:95]
	v_mfma_f32_32x32x16_bf16 v[32:47], v[132:135], v[156:159], v[32:47]
	s_waitcnt lgkmcnt(0)
	v_mfma_f32_32x32x16_bf16 v[64:79], v[144:147], v[160:163], v[64:79]
	v_mfma_f32_32x32x16_bf16 v[48:63], v[132:135], v[160:163], v[48:63]
	s_nop 0
	ds_read_b64_tr_b16 v[132:133], v218 offset:28672
	ds_read_b64_tr_b16 v[134:135], v239 offset:30720
	ds_read_b64_tr_b16 v[140:141], v240 offset:28672
	ds_read_b64_tr_b16 v[142:143], v241 offset:30720
	ds_read_b64_tr_b16 v[144:145], v248 offset:28672
	ds_read_b64_tr_b16 v[146:147], v249 offset:30720
	ds_read_b64_tr_b16 v[148:149], v250 offset:28672
	ds_read_b64_tr_b16 v[150:151], v251 offset:30720
	s_waitcnt lgkmcnt(6)
	v_mfma_f32_32x32x16_bf16 v[112:127], v[128:131], v[132:135], v[112:127]
	v_mfma_f32_32x32x16_bf16 v[0:15], v[136:139], v[132:135], v[0:15]
	ds_read_b128 v[132:135], v222
	ds_read_b128 v[174:177], v222 offset:3072
	s_waitcnt lgkmcnt(6)
	v_mfma_f32_32x32x16_bf16 v[96:111], v[128:131], v[140:143], v[96:111]
	v_mfma_f32_32x32x16_bf16 v[16:31], v[136:139], v[140:143], v[16:31]
	ds_read_b128 v[140:143], v222 offset:2048
	s_waitcnt lgkmcnt(5)
	v_mfma_f32_32x32x16_bf16 v[80:95], v[128:131], v[144:147], v[80:95]
	v_mfma_f32_32x32x16_bf16 v[32:47], v[136:139], v[144:147], v[32:47]
	s_waitcnt lgkmcnt(3)
	v_mfma_f32_32x32x16_bf16 v[64:79], v[128:131], v[148:151], v[64:79]
	v_mfma_f32_32x32x16_bf16 v[48:63], v[136:139], v[148:151], v[48:63]
	ds_read_b128 v[136:139], v222 offset:1024
	s_waitcnt vmcnt(0)
	s_add_u32 s30, s30, 0x50000
	s_addc_u32 s31, s31, 0
	s_cmp_eq_u32 s45, s38
	s_mov_b32 s8, s39
	s_barrier
	s_cbranch_scc1 .LBB0_383
	s_branch .Lat2_top_O
.LBB0_379:
	ds_read_b128 v[128:131], v217
	ds_read_b128 v[160:163], v236
	ds_read_b128 v[166:169], v237
	ds_read_b128 v[170:173], v238
	s_add_i32 s38, s38, 1
	s_cmp_lt_u32 s38, s45
	s_mov_b64 s[0:1], -1
	s_cbranch_scc1 .LBB0_381
	s_add_i32 s39, s8, 0x8000
	s_mov_b64 s[0:1], 0

; #define SB() __builtin_amdgcn_sched_barrier(0)
; #define EXPACK(sc_, rbq_, p0_, p1_) do { float ps_ = 0.f; \
;                 _Pragma("unroll") for (int r = 0; r < 16; ++r) { sc_[r] = __builtin_amdgcn_exp2f(SHIFT ? sc_[r] - bound2 : sc_[r]); ps_ += sc_[r]; } \
;                 lsum[rbq_] += ps_; p0_ = pack8(sc_, 0); p1_ = pack8(sc_, 1); } while (0)
; #define BLOAD(B_, ks_) do { asm volatile("" : "+v"(v0l)); _Pragma("unroll") for (int cb = 0; cb < 4; ++cb) B_[cb] = BFRAG(ks_, cb); SB(); } while (0)
; #define PVMMA(B_, pA_, pB_) do { _Pragma("unroll") for (int cb = 0; cb < 4; ++cb) { o[0][cb] = MFMA32(pA_, B_[cb], o[0][cb]); o[1][cb] = MFMA32(pB_, B_[cb], o[1][cb]); } } while (0)
; template <bool SHIFT> DI void phase_attn2(const Params& p, const Grp& G, int layer, LAS unsigned char* lds, int tid, int wave, int lane, int vcu, bool dry) {
;     ...
;             {
;                 f32x16 s0, s1; bf16x8 pa00, pa01, pa10, pa11; bf16x8 kfs[4], qfs[4];
;                 CHAIN(s0, 0, 0, true, true); CHAIN(s1, 0, 1, false, true);
;                 EXPACK(s0, 0, pa00, pa01); EXPACK(s1, 1, pa10, pa11);
;                 SB();
;                 CHAIN(s1, 1, 1, true, false); CHAIN(s0, 1, 0, false, true);
;                 bf16x8 pb00, pb01, pb10, pb11; bf16x8 B[4];
;                 BLOAD(B, 0);
;                 PVMMA(B, pa00, pa10); EXPACK(s0, 0, pb00, pb01);
.Lat2_body_O:
	s_waitcnt lgkmcnt(0)
	v_mfma_f32_32x32x16_bf16 v[144:159], v[128:131], v[132:135], 0
	v_mfma_f32_32x32x16_bf16 v[144:159], v[160:163], v[136:139], v[144:159]
	v_mfma_f32_32x32x16_bf16 v[144:159], v[166:169], v[140:143], v[144:159]
	v_mfma_f32_32x32x16_bf16 v[144:159], v[170:173], v[174:177], v[144:159]
	ds_read_b128 v[174:177], v222 offset:4096
	ds_read_b128 v[178:181], v222 offset:5120
	ds_read_b128 v[182:185], v222 offset:6144
	ds_read_b128 v[224:227], v222 offset:7168
	s_waitcnt lgkmcnt(0)
	v_mfma_f32_32x32x16_bf16 v[128:143], v[128:131], v[174:177], 0
	v_mfma_f32_32x32x16_bf16 v[128:143], v[160:163], v[178:181], v[128:143]
	v_mfma_f32_32x32x16_bf16 v[128:143], v[166:169], v[182:185], v[128:143]
	v_mfma_f32_32x32x16_bf16 v[128:143], v[170:173], v[224:227], v[128:143]
	ds_read_b128 v[170:173], v236 offset:40960
	ds_read_b128 v[228:231], v237 offset:40960
	ds_read_b128 v[232:235], v238 offset:40960
	v_exp_f32_e32 v144, v144
	v_exp_f32_e32 v145, v145
	v_exp_f32_e32 v146, v146
	v_exp_f32_e32 v147, v147
	v_exp_f32_e32 v148, v148
	v_exp_f32_e32 v149, v149
	v_exp_f32_e32 v150, v150
	v_exp_f32_e32 v188, v151
	v_exp_f32_e32 v208, v152
	v_exp_f32_e32 v206, v153
	v_exp_f32_e32 v204, v154
	v_exp_f32_e32 v202, v155
	v_exp_f32_e32 v200, v156
	v_exp_f32_e32 v198, v157
	v_exp_f32_e32 v196, v158
	v_exp_f32_e32 v190, v159
	v_exp_f32_e32 v189, v135
	v_add_f32_e32 v135, v145, v144
	v_exp_f32_e32 v128, v128
	v_exp_f32_e32 v129, v129
	v_exp_f32_e32 v130, v130
	v_exp_f32_e32 v131, v131
	v_exp_f32_e32 v132, v132
	v_exp_f32_e32 v133, v133
	v_exp_f32_e32 v134, v134
	v_add_f32_e32 v135, v146, v135
	v_add_f32_e32 v135, v147, v135
	v_add_f32_e32 v135, v148, v135
	v_add_f32_e32 v135, v149, v135
	v_cvt_pk_bf16_f32 v160, v144, v145
	v_cvt_pk_bf16_f32 v161, v146, v147
	v_cvt_pk_bf16_f32 v162, v148, v149
	v_cvt_pk_bf16_f32 v163, v150, v188
	v_exp_f32_e32 v209, v136
	v_exp_f32_e32 v207, v137
	v_exp_f32_e32 v205, v138
	v_exp_f32_e32 v203, v139
	v_exp_f32_e32 v201, v140
	v_exp_f32_e32 v199, v141
	v_exp_f32_e32 v197, v142
	v_exp_f32_e32 v191, v143
	v_add_f32_e32 v210, v150, v135
	v_cvt_pk_bf16_f32 v166, v128, v129
	v_cvt_pk_bf16_f32 v167, v130, v131
	v_cvt_pk_bf16_f32 v168, v132, v133
	v_cvt_pk_bf16_f32 v169, v134, v189
	ds_read_b128 v[144:147], v217 offset:40960
	v_add_f32_e32 v128, v129, v128
	v_add_f32_e32 v128, v130, v128
	v_add_f32_e32 v128, v131, v128
	v_add_f32_e32 v128, v132, v128
	v_add_f32_e32 v128, v133, v128
	v_add_f32_e32 v211, v134, v128
	s_waitcnt lgkmcnt(0)
	v_mfma_f32_32x32x16_bf16 v[128:143], v[144:147], v[174:177], 0
	v_mfma_f32_32x32x16_bf16 v[128:143], v[170:173], v[178:181], v[128:143]
	v_mfma_f32_32x32x16_bf16 v[128:143], v[228:231], v[182:185], v[128:143]
	v_mfma_f32_32x32x16_bf16 v[128:143], v[232:235], v[224:227], v[128:143]
	ds_read_b128 v[148:151], v222
	ds_read_b128 v[174:177], v222 offset:1024
	ds_read_b128 v[178:181], v222 offset:2048
	ds_read_b128 v[182:185], v222 offset:3072
	s_waitcnt lgkmcnt(0)
	v_mfma_f32_32x32x16_bf16 v[144:159], v[144:147], v[148:151], 0
	v_mfma_f32_32x32x16_bf16 v[144:159], v[170:173], v[174:177], v[144:159]
	v_mfma_f32_32x32x16_bf16 v[144:159], v[228:231], v[178:181], v[144:159]
	v_mfma_f32_32x32x16_bf16 v[144:159], v[232:235], v[182:185], v[144:159]
	s_nop 4
	ds_read_b64_tr_b16 v[170:171], v218 offset:49152
	ds_read_b64_tr_b16 v[172:173], v239 offset:51200
	ds_read_b64_tr_b16 v[174:175], v240 offset:49152
	ds_read_b64_tr_b16 v[176:177], v241 offset:51200
	ds_read_b64_tr_b16 v[178:179], v248 offset:49152
	ds_read_b64_tr_b16 v[180:181], v249 offset:51200
	ds_read_b64_tr_b16 v[182:183], v250 offset:49152
	ds_read_b64_tr_b16 v[184:185], v251 offset:51200
	v_exp_f32_e32 v144, v144
	s_waitcnt lgkmcnt(6)
	v_mfma_f32_32x32x16_bf16 v[112:127], v[160:163], v[170:173], v[112:127]
	v_exp_f32_e32 v145, v145
	v_exp_f32_e32 v146, v146
	v_exp_f32_e32 v147, v147
	v_exp_f32_e32 v148, v148
	v_exp_f32_e32 v149, v149
	v_mfma_f32_32x32x16_bf16 v[0:15], v[166:169], v[170:173], v[0:15]
	v_exp_f32_e32 v170, v151
	v_exp_f32_e32 v172, v154
	s_waitcnt lgkmcnt(4)
	v_mfma_f32_32x32x16_bf16 v[96:111], v[160:163], v[174:177], v[96:111]
	v_mfma_f32_32x32x16_bf16 v[16:31], v[166:169], v[174:177], v[16:31]
	v_exp_f32_e32 v174, v153
	v_exp_f32_e32 v176, v156
	s_waitcnt lgkmcnt(2)
	v_mfma_f32_32x32x16_bf16 v[80:95], v[160:163], v[178:181], v[80:95]
	v_mfma_f32_32x32x16_bf16 v[32:47], v[166:169], v[178:181], v[32:47]
	v_exp_f32_e32 v178, v155
	v_exp_f32_e32 v180, v158
	s_waitcnt lgkmcnt(0)
	v_mfma_f32_32x32x16_bf16 v[64:79], v[160:163], v[182:185], v[64:79]
	v_add_f32_e32 v160, v145, v144
	v_add_f32_e32 v160, v146, v160
	v_add_f32_e32 v160, v147, v160
	v_add_f32_e32 v160, v148, v160
	v_add_f32_e32 v186, v149, v160
	v_cvt_pk_bf16_f32 v144, v144, v145
	v_mfma_f32_32x32x16_bf16 v[48:63], v[166:169], v[182:185], v[48:63]
	v_exp_f32_e32 v166, v150
	v_exp_f32_e32 v168, v152
	v_exp_f32_e32 v182, v157
	v_exp_f32_e32 v184, v159
	v_cvt_pk_bf16_f32 v145, v146, v147
	v_cvt_pk_bf16_f32 v146, v148, v149
	s_nop 0
	ds_read_b64_tr_b16 v[160:161], v218 offset:53248
	ds_read_b64_tr_b16 v[162:163], v239 offset:55296
	ds_read_b64_tr_b16 v[156:157], v240 offset:53248
	ds_read_b64_tr_b16 v[158:159], v241 offset:55296
	ds_read_b64_tr_b16 v[152:153], v248 offset:53248
	ds_read_b64_tr_b16 v[154:155], v249 offset:55296
	ds_read_b64_tr_b16 v[148:149], v250 offset:53248
	ds_read_b64_tr_b16 v[150:151], v251 offset:55296
	v_exp_f32_e32 v223, v128
	v_exp_f32_e32 v224, v129
	v_exp_f32_e32 v225, v130
	v_exp_f32_e32 v226, v131
	v_exp_f32_e32 v227, v132
	v_add_f32_e32 v128, v224, v223
	v_exp_f32_e32 v228, v133
	v_exp_f32_e32 v167, v134
	v_exp_f32_e32 v171, v135
	v_cvt_pk_bf16_f32 v132, v208, v206
	v_cvt_pk_bf16_f32 v133, v204, v202
	v_cvt_pk_bf16_f32 v134, v200, v198
	v_cvt_pk_bf16_f32 v135, v196, v190
	v_add_f32_e32 v128, v225, v128
	v_exp_f32_e32 v169, v136
	v_exp_f32_e32 v175, v137
	v_exp_f32_e32 v173, v138
	v_exp_f32_e32 v179, v139
	v_cvt_pk_bf16_f32 v136, v209, v207
	v_cvt_pk_bf16_f32 v137, v205, v203
	v_cvt_pk_bf16_f32 v138, v201, v199
	v_cvt_pk_bf16_f32 v139, v197, v191
	v_add_f32_e32 v128, v226, v128
	v_add_f32_e32 v128, v227, v128
	v_add_f32_e32 v187, v228, v128
	v_pk_add_f32 v[128:129], v[188:189], v[210:211]
	s_waitcnt lgkmcnt(6)
; #define LAS __attribute__((address_space(3)))
; #define SB() __builtin_amdgcn_sched_barrier(0)
; #define BLOAD(B_, ks_) do { asm volatile("" : "+v"(v0l)); _Pragma("unroll") for (int cb = 0; cb < 4; ++cb) B_[cb] = BFRAG(ks_, cb); SB(); } while (0)
; #define PVMMA(B_, pA_, pB_) do { _Pragma("unroll") for (int cb = 0; cb < 4; ++cb) { o[0][cb] = MFMA32(pA_, B_[cb], o[0][cb]); o[1][cb] = MFMA32(pB_, B_[cb], o[1][cb]); } } while (0)
; template <bool SHIFT> DI void phase_attn2(const Params& p, const Grp& G, int layer, LAS unsigned char* lds, int tid, int wave, int lane, int vcu, bool dry) {
;     ...
;         for (int t = 0; t < NT; ++t) {
;             unsigned dfl = doff0; asm volatile("" : "+v"(dfl));
;             if (t + 1 < NT) AT2_DMA(t + 1, (t + 1) & 1);
;             const LAS unsigned char* Kt = lds + (t & 1) * AT2_BUF; const LAS unsigned char* Vt = Kt + AT2_TILE;
;             int k0l = k0, v0l = v0; asm volatile("" : "+v"(k0l), "+v"(v0l));
;     ...
;                 BLOAD(B, 3);
;                 PVMMA(B, pb01, pb11);
;                 SB();
;             }
;     ...
;             asm volatile("s_waitcnt vmcnt(0)" ::: "memory");
;             __syncthreads();
	v_mfma_f32_32x32x16_bf16 v[112:127], v[132:135], v[160:163], v[112:127]
	v_add_f32_e64 v128, v208, v128
	v_add_f32_e64 v129, v209, v129
	v_exp_f32_e32 v177, v140
	v_pk_add_f32 v[128:129], v[206:207], v[128:129]
	v_exp_f32_e32 v183, v141
	v_pk_add_f32 v[128:129], v[204:205], v[128:129]
	v_exp_f32_e32 v181, v142
	v_pk_add_f32 v[128:129], v[202:203], v[128:129]
	s_waitcnt lgkmcnt(4)
	v_mfma_f32_32x32x16_bf16 v[96:111], v[132:135], v[156:159], v[96:111]
	v_exp_f32_e32 v185, v143
	v_pk_add_f32 v[128:129], v[200:201], v[128:129]
	v_cvt_pk_bf16_f32 v147, v166, v170
	v_pk_add_f32 v[128:129], v[198:199], v[128:129]
	v_cvt_pk_bf16_f32 v130, v176, v182
	v_pk_add_f32 v[128:129], v[196:197], v[128:129]
	v_cvt_pk_bf16_f32 v131, v180, v184
	s_waitcnt lgkmcnt(2)
	v_mfma_f32_32x32x16_bf16 v[80:95], v[132:135], v[152:155], v[80:95]
	v_add_f32_e64 v128, v190, v128
	v_add_f32_e64 v129, v191, v129
	v_add_f32_e64 v140, v164, v128
	v_add_f32_e64 v141, v165, v129
	v_cvt_pk_bf16_f32 v128, v168, v174
	v_cvt_pk_bf16_f32 v129, v172, v178
	s_waitcnt lgkmcnt(0)
	v_mfma_f32_32x32x16_bf16 v[64:79], v[132:135], v[148:151], v[64:79]
	v_add_f32_e64 v132, v166, v186
	v_add_f32_e64 v133, v167, v187
	v_cvt_pk_bf16_f32 v134, v227, v228
	v_add_f32_e64 v132, v170, v132
	v_add_f32_e64 v133, v171, v133
	v_cvt_pk_bf16_f32 v135, v167, v171
	v_pk_add_f32 v[132:133], v[168:169], v[132:133]
	s_nop 0
	v_pk_add_f32 v[132:133], v[174:175], v[132:133]
	v_mfma_f32_32x32x16_bf16 v[0:15], v[136:139], v[160:163], v[0:15]
	v_add_f32_e64 v132, v172, v132
	v_add_f32_e64 v133, v173, v133
	v_add_f32_e64 v132, v178, v132
	v_add_f32_e64 v133, v179, v133
	v_add_f32_e64 v132, v176, v132
	v_add_f32_e64 v133, v177, v133
	v_pk_add_f32 v[132:133], v[182:183], v[132:133]
	v_mfma_f32_32x32x16_bf16 v[16:31], v[136:139], v[156:159], v[16:31]
	v_add_f32_e64 v132, v180, v132
	v_add_f32_e64 v133, v181, v133
	v_add_f32_e64 v142, v184, v132
	v_add_f32_e64 v143, v185, v133
	v_cvt_pk_bf16_f32 v132, v223, v224
	v_cvt_pk_bf16_f32 v133, v225, v226
	v_mfma_f32_32x32x16_bf16 v[32:47], v[136:139], v[152:155], v[32:47]
	v_mfma_f32_32x32x16_bf16 v[48:63], v[136:139], v[148:151], v[48:63]
	v_cvt_pk_bf16_f32 v136, v169, v175
	v_cvt_pk_bf16_f32 v137, v173, v179
	v_cvt_pk_bf16_f32 v138, v177, v183
	v_cvt_pk_bf16_f32 v139, v181, v185
	s_nop 0
	ds_read_b64_tr_b16 v[148:149], v218 offset:57344
	ds_read_b64_tr_b16 v[150:151], v239 offset:59392
	ds_read_b64_tr_b16 v[152:153], v240 offset:57344
	ds_read_b64_tr_b16 v[154:155], v241 offset:59392
	ds_read_b64_tr_b16 v[156:157], v248 offset:57344
	ds_read_b64_tr_b16 v[158:159], v249 offset:59392
	ds_read_b64_tr_b16 v[160:161], v250 offset:57344
	ds_read_b64_tr_b16 v[162:163], v251 offset:59392
	s_waitcnt lgkmcnt(6)
	v_mfma_f32_32x32x16_bf16 v[112:127], v[144:147], v[148:151], v[112:127]
	v_add_f32_e64 v164, v140, v142
	v_add_f32_e64 v165, v141, v143
	v_mfma_f32_32x32x16_bf16 v[0:15], v[132:135], v[148:151], v[0:15]
	s_waitcnt lgkmcnt(4)
	v_mfma_f32_32x32x16_bf16 v[96:111], v[144:147], v[152:155], v[96:111]
	v_mfma_f32_32x32x16_bf16 v[16:31], v[132:135], v[152:155], v[16:31]
	s_waitcnt lgkmcnt(2)
	v_mfma_f32_32x32x16_bf16 v[80:95], v[144:147], v[156:159], v[80:95]
	v_mfma_f32_32x32x16_bf16 v[32:47], v[132:135], v[156:159], v[32:47]
	s_waitcnt lgkmcnt(0)
	v_mfma_f32_32x32x16_bf16 v[64:79], v[144:147], v[160:163], v[64:79]
	v_mfma_f32_32x32x16_bf16 v[48:63], v[132:135], v[160:163], v[48:63]
	s_nop 0
	ds_read_b64_tr_b16 v[132:133], v218 offset:61440
	ds_read_b64_tr_b16 v[134:135], v239 offset:63488
	ds_read_b64_tr_b16 v[140:141], v240 offset:61440
	ds_read_b64_tr_b16 v[142:143], v241 offset:63488
	ds_read_b64_tr_b16 v[144:145], v248 offset:61440
	ds_read_b64_tr_b16 v[146:147], v249 offset:63488
	ds_read_b64_tr_b16 v[148:149], v250 offset:61440
	ds_read_b64_tr_b16 v[150:151], v251 offset:63488
	s_waitcnt lgkmcnt(6)
	v_mfma_f32_32x32x16_bf16 v[112:127], v[128:131], v[132:135], v[112:127]
	v_mfma_f32_32x32x16_bf16 v[0:15], v[136:139], v[132:135], v[0:15]
	ds_read_b128 v[132:135], v222
	ds_read_b128 v[174:177], v222 offset:3072
	s_waitcnt lgkmcnt(6)
	v_mfma_f32_32x32x16_bf16 v[96:111], v[128:131], v[140:143], v[96:111]
	v_mfma_f32_32x32x16_bf16 v[16:31], v[136:139], v[140:143], v[16:31]
	ds_read_b128 v[140:143], v222 offset:2048
	s_waitcnt lgkmcnt(5)
	v_mfma_f32_32x32x16_bf16 v[80:95], v[128:131], v[144:147], v[80:95]
	v_mfma_f32_32x32x16_bf16 v[32:47], v[136:139], v[144:147], v[32:47]
	s_waitcnt lgkmcnt(3)
	v_mfma_f32_32x32x16_bf16 v[64:79], v[128:131], v[148:151], v[64:79]
	v_mfma_f32_32x32x16_bf16 v[48:63], v[136:139], v[148:151], v[48:63]
	ds_read_b128 v[136:139], v222 offset:1024
	s_waitcnt vmcnt(0)
	s_add_u32 s30, s30, 0x50000
	s_addc_u32 s31, s31, 0
	s_cmp_eq_u32 s45, s38
	s_mov_b32 s8, s39
	s_barrier
	s_cbranch_scc1 .LBB0_383
	s_branch .LBB0_379
.Lat2_top_O:
	ds_read_b128 v[128:131], v217 offset:32768
	ds_read_b128 v[160:163], v236 offset:32768
	ds_read_b128 v[166:169], v237 offset:32768
	ds_read_b128 v[170:173], v238 offset:32768
	s_add_i32 s38, s38, 1
	s_cmp_lt_u32 s38, s45
	s_mov_b64 s[0:1], -1
	s_cbranch_scc1 .Lat2_skip_O
	s_add_i32 s39, s8, 0x8000
	s_mov_b64 s[0:1], 0

; template <bool SHIFT> DI void phase_attn2(const Params& p, const Grp& G, int layer, LAS unsigned char* lds, int tid, int wave, int lane, int vcu, bool dry) {
;     ...
;         lsum[0] += __shfl_xor(lsum[0], 32); lsum[1] += __shfl_xor(lsum[1], 32);
;         int lanev = (int)__builtin_amdgcn_mbcnt_hi(~0u, __builtin_amdgcn_mbcnt_lo(~0u, 0u)); asm volatile("" : "+v"(lanev));
;         const int hiv = lanev >> 5, l31v = lanev & 31;
;         if (hiv == 0) { lscr[l31v] = lsum[0]; lscr[32 + l31v] = lsum[1]; }
.LBB0_383:
	s_waitcnt lgkmcnt(0)
	ds_bpermute_b32 v129, v216, v164
	ds_bpermute_b32 v130, v216, v165
	v_mov_b32_e32 v128, v245
	s_nop 0
	v_and_b32_e32 v157, 31, v128
	v_cmp_gt_u32_e32 vcc, 32, v128
	s_and_saveexec_b64 s[0:1], vcc
	s_cbranch_execz .LBB0_385
	s_waitcnt lgkmcnt(1)
	v_add_f32_e32 v129, v164, v129
	v_lshl_add_u32 v131, v157, 2, s12
	s_waitcnt lgkmcnt(0)
	v_add_f32_e32 v130, v165, v130
	v_lshl_add_u32 v132, v128, 2, s12
	ds_write_b32 v131, v129
	ds_write_b32 v132, v130 offset:128
